# scan-states wait done by the (idle) leader wave before the workgroup barrier of the P3->P4 seam instead of after it
# speedup vs baseline: 1.0194x; 1.0020x over previous
.Lp3_arrd:
	s_mov_b64 exec, s[100:101]
	v_readlane_b32 s99, v254, 25
	s_nop 3
	s_cmp_lg_u32 s99, 0
	s_cbranch_scc1 .Lp3_noarr
	s_mov_b64 s[100:101], exec
	s_mov_b64 exec, 1
	v_mov_b32_e32 v0, 0x21004
	ds_read_b32 v1, v0
	v_mov_b32_e32 v0, 0xfa0e900
	s_mov_b32 s99, 0
	s_waitcnt lgkmcnt(0)
	buffer_inv sc1

.Lp3_noarr:
	s_waitcnt vmcnt(0)
	s_and_b64 vcc, exec, s[66:67]
	s_barrier
	s_cbranch_vccnz .LBB0_592
	s_cmp_lg_u32 s98, 0
	s_cbranch_scc0 .Lb4_orig
	s_branch .LBB0_592
